# chunk-carry scan phase loads nt as well
# baseline (speedup 1.0000x reference)
; DEVI int otid() { int t = threadIdx.x; asm volatile("" : "+v"(t)); return t; }
; DEVI int obid() { int t = blockIdx.x; asm volatile("" : "+s"(t)); return t; }
; DEVI float bf2f(u16 b) { return __uint_as_float(((unsigned)b) << 16); }
; DEVI u32x2 pk4(f32x4 v) { u32x2 r; r.x = cvt_pk(v[0], v[1]); r.y = cvt_pk(v[2], v[3]); return r; }
; DEVI void mix_scan_phase(const MixArgs a, bool with_n) {
;     const int gt = obid() * 512 + otid(), nthr = gridDim.x * 512;
;     for (int e = gt; e < 16 * 256 * 32; e += nthr) { const int dk4 = (e & 31) * 4, dv = (e >> 5) & 255, bh = e >> 13;
;         f32x4 run = (f32x4){0.f, 0.f, 0.f, 0.f};
; #pragma unroll 16
;         for (int c = 0; c < NCH; ++c) { const size_t it = (size_t)bh * NCH + c; u16* sp = a.states + (it * 256 + dv) * 128 + dk4;
;             const f32x4 d = *(const f32x4*)(a.dec + it * 128 + dk4); const bf16x4 x = *(const bf16x4*)sp;
;             *(u32x2*)sp = pk4(run);
; #pragma unroll
;             for (int j = 0; j < 4; ++j) run[j] = d[j] * run[j] + bf2f((u16)x[j]); } }
.LBB0_627:
	v_lshl_add_u64 v[6:7], s[20:21], 0, v[0:1]
	v_add_co_u32_e32 v10, vcc, 0x1d600000, v6
	v_lshl_add_u64 v[4:5], s[20:21], 0, v[2:3]
	s_nop 0
	v_addc_co_u32_e32 v11, vcc, 0, v7, vcc
	v_add_co_u32_e32 v4, vcc, 0x19380000, v4
	s_mov_b64 s[0:1], 0x10000
	s_nop 0
	v_addc_co_u32_e32 v5, vcc, 0, v5, vcc
	v_mov_b64_e32 v[24:25], v[4:5]
	v_mov_b64_e32 v[26:27], v[4:5]
	global_load_dwordx4 v[56:59], v[10:11], off nt
	global_load_dwordx2 v[134:135], v[24:25], off nt
	v_lshl_add_u64 v[24:25], v[24:25], 0, s[0:1]
	global_load_dwordx4 v[60:63], v[10:11], off offset:512 nt
	global_load_dwordx2 v[136:137], v[24:25], off nt
	v_lshl_add_u64 v[24:25], v[24:25], 0, s[0:1]
	global_load_dwordx4 v[64:67], v[10:11], off offset:1024 nt
	global_load_dwordx2 v[138:139], v[24:25], off nt
	v_lshl_add_u64 v[24:25], v[24:25], 0, s[0:1]
	global_load_dwordx4 v[68:71], v[10:11], off offset:1536 nt
	global_load_dwordx2 v[140:141], v[24:25], off nt
	v_lshl_add_u64 v[24:25], v[24:25], 0, s[0:1]
	global_load_dwordx4 v[72:75], v[10:11], off offset:2048 nt
	global_load_dwordx2 v[142:143], v[24:25], off nt
	v_lshl_add_u64 v[24:25], v[24:25], 0, s[0:1]
	global_load_dwordx4 v[76:79], v[10:11], off offset:2560 nt
	global_load_dwordx2 v[144:145], v[24:25], off nt
	v_lshl_add_u64 v[24:25], v[24:25], 0, s[0:1]
	global_load_dwordx4 v[80:83], v[10:11], off offset:3072 nt
	global_load_dwordx2 v[148:149], v[24:25], off nt
	v_lshl_add_u64 v[24:25], v[24:25], 0, s[0:1]
	global_load_dwordx4 v[88:91], v[10:11], off offset:3584 nt
	global_load_dwordx2 v[150:151], v[24:25], off nt
	v_lshl_add_u64 v[24:25], v[24:25], 0, s[0:1]
	v_add_co_u32_e32 v10, vcc, 0x1000, v10
	s_nop 1
	v_addc_co_u32_e32 v11, vcc, 0, v11, vcc
	s_waitcnt vmcnt(0)
	s_mov_b32 s6, 4
.Lms_loop:
	global_load_dwordx4 v[92:95], v[10:11], off nt
	global_load_dwordx2 v[152:153], v[24:25], off nt
	v_lshl_add_u64 v[24:25], v[24:25], 0, s[0:1]
	global_load_dwordx4 v[100:103], v[10:11], off offset:512 nt
	global_load_dwordx2 v[162:163], v[24:25], off nt
	v_lshl_add_u64 v[24:25], v[24:25], 0, s[0:1]
	global_load_dwordx4 v[104:107], v[10:11], off offset:1024 nt
	global_load_dwordx2 v[164:165], v[24:25], off nt
	v_lshl_add_u64 v[24:25], v[24:25], 0, s[0:1]
	global_load_dwordx4 v[108:111], v[10:11], off offset:1536 nt
	global_load_dwordx2 v[176:177], v[24:25], off nt
	v_lshl_add_u64 v[24:25], v[24:25], 0, s[0:1]
	global_load_dwordx4 v[112:115], v[10:11], off offset:2048 nt
	global_load_dwordx2 v[178:179], v[24:25], off nt
	v_lshl_add_u64 v[24:25], v[24:25], 0, s[0:1]
	global_load_dwordx4 v[116:119], v[10:11], off offset:2560 nt
	global_load_dwordx2 v[180:181], v[24:25], off nt
	v_lshl_add_u64 v[24:25], v[24:25], 0, s[0:1]
	global_load_dwordx4 v[126:129], v[10:11], off offset:3072 nt
	global_load_dwordx2 v[182:183], v[24:25], off nt
	v_lshl_add_u64 v[24:25], v[24:25], 0, s[0:1]
	global_load_dwordx4 v[130:133], v[10:11], off offset:3584 nt
	global_load_dwordx2 v[120:121], v[24:25], off nt
	v_lshl_add_u64 v[24:25], v[24:25], 0, s[0:1]
	v_add_co_u32_e32 v10, vcc, 0x1000, v10
	s_nop 1
	v_addc_co_u32_e32 v11, vcc, 0, v11, vcc
	v_cvt_pk_bf16_f32 v28, v12, v13
	v_cvt_pk_bf16_f32 v29, v14, v15
	global_store_dwordx2 v[26:27], v[28:29], off
	v_lshl_add_u64 v[26:27], v[26:27], 0, s[0:1]
	s_waitcnt vmcnt(39)
	v_and_b32_e32 v21, 0xffff0000, v134
	v_lshlrev_b32_e32 v20, 16, v134
	v_and_b32_e32 v23, 0xffff0000, v135
	v_lshlrev_b32_e32 v22, 16, v135
	v_pk_fma_f32 v[12:13], v[12:13], v[56:57], v[20:21]
	v_pk_fma_f32 v[14:15], v[14:15], v[58:59], v[22:23]
	v_cvt_pk_bf16_f32 v28, v12, v13
	v_cvt_pk_bf16_f32 v29, v14, v15
	global_store_dwordx2 v[26:27], v[28:29], off
	v_lshl_add_u64 v[26:27], v[26:27], 0, s[0:1]
	s_waitcnt vmcnt(38)
	v_and_b32_e32 v21, 0xffff0000, v136
	v_lshlrev_b32_e32 v20, 16, v136
	v_and_b32_e32 v23, 0xffff0000, v137
	v_lshlrev_b32_e32 v22, 16, v137
	v_pk_fma_f32 v[12:13], v[12:13], v[60:61], v[20:21]
	v_pk_fma_f32 v[14:15], v[14:15], v[62:63], v[22:23]
	v_cvt_pk_bf16_f32 v28, v12, v13
	v_cvt_pk_bf16_f32 v29, v14, v15
	global_store_dwordx2 v[26:27], v[28:29], off
	v_lshl_add_u64 v[26:27], v[26:27], 0, s[0:1]
	s_waitcnt vmcnt(37)
	v_and_b32_e32 v21, 0xffff0000, v138
	v_lshlrev_b32_e32 v20, 16, v138
	v_and_b32_e32 v23, 0xffff0000, v139
	v_lshlrev_b32_e32 v22, 16, v139
	v_pk_fma_f32 v[12:13], v[12:13], v[64:65], v[20:21]
	v_pk_fma_f32 v[14:15], v[14:15], v[66:67], v[22:23]
	v_cvt_pk_bf16_f32 v28, v12, v13
	v_cvt_pk_bf16_f32 v29, v14, v15
	global_store_dwordx2 v[26:27], v[28:29], off
	v_lshl_add_u64 v[26:27], v[26:27], 0, s[0:1]
	s_waitcnt vmcnt(36)
	v_and_b32_e32 v21, 0xffff0000, v140
	v_lshlrev_b32_e32 v20, 16, v140
	v_and_b32_e32 v23, 0xffff0000, v141
	v_lshlrev_b32_e32 v22, 16, v141
	v_pk_fma_f32 v[12:13], v[12:13], v[68:69], v[20:21]
	v_pk_fma_f32 v[14:15], v[14:15], v[70:71], v[22:23]
	v_cvt_pk_bf16_f32 v28, v12, v13
	v_cvt_pk_bf16_f32 v29, v14, v15
	global_store_dwordx2 v[26:27], v[28:29], off
	v_lshl_add_u64 v[26:27], v[26:27], 0, s[0:1]
	s_waitcnt vmcnt(35)
	v_and_b32_e32 v21, 0xffff0000, v142
	v_lshlrev_b32_e32 v20, 16, v142
	v_and_b32_e32 v23, 0xffff0000, v143
	v_lshlrev_b32_e32 v22, 16, v143
	v_pk_fma_f32 v[12:13], v[12:13], v[72:73], v[20:21]
	v_pk_fma_f32 v[14:15], v[14:15], v[74:75], v[22:23]
	v_cvt_pk_bf16_f32 v28, v12, v13
	v_cvt_pk_bf16_f32 v29, v14, v15
	global_store_dwordx2 v[26:27], v[28:29], off
	v_lshl_add_u64 v[26:27], v[26:27], 0, s[0:1]
	s_waitcnt vmcnt(34)
	v_and_b32_e32 v21, 0xffff0000, v144
	v_lshlrev_b32_e32 v20, 16, v144
	v_and_b32_e32 v23, 0xffff0000, v145
	v_lshlrev_b32_e32 v22, 16, v145
	v_pk_fma_f32 v[12:13], v[12:13], v[76:77], v[20:21]
	v_pk_fma_f32 v[14:15], v[14:15], v[78:79], v[22:23]
	v_cvt_pk_bf16_f32 v28, v12, v13
	v_cvt_pk_bf16_f32 v29, v14, v15
	global_store_dwordx2 v[26:27], v[28:29], off
	v_lshl_add_u64 v[26:27], v[26:27], 0, s[0:1]
	s_waitcnt vmcnt(33)
	v_and_b32_e32 v21, 0xffff0000, v148
	v_lshlrev_b32_e32 v20, 16, v148
	v_and_b32_e32 v23, 0xffff0000, v149
	v_lshlrev_b32_e32 v22, 16, v149
	v_pk_fma_f32 v[12:13], v[12:13], v[80:81], v[20:21]
	v_pk_fma_f32 v[14:15], v[14:15], v[82:83], v[22:23]
	v_cvt_pk_bf16_f32 v28, v12, v13
	v_cvt_pk_bf16_f32 v29, v14, v15
	global_store_dwordx2 v[26:27], v[28:29], off
	v_lshl_add_u64 v[26:27], v[26:27], 0, s[0:1]
	s_waitcnt vmcnt(32)
	v_and_b32_e32 v21, 0xffff0000, v150
	v_lshlrev_b32_e32 v20, 16, v150
	v_and_b32_e32 v23, 0xffff0000, v151
	v_lshlrev_b32_e32 v22, 16, v151
	v_pk_fma_f32 v[12:13], v[12:13], v[88:89], v[20:21]
	v_pk_fma_f32 v[14:15], v[14:15], v[90:91], v[22:23]
	s_sub_i32 s6, s6, 1
	s_cmp_eq_u32 s6, 0
	s_cbranch_scc1 .Lms_last
; DEVI float bf2f(u16 b) { return __uint_as_float(((unsigned)b) << 16); }
; DEVI u32x2 pk4(f32x4 v) { u32x2 r; r.x = cvt_pk(v[0], v[1]); r.y = cvt_pk(v[2], v[3]); return r; }
; DEVI void mix_scan_phase(const MixArgs a, bool with_n) {
;     ...
;     for (int e = gt; e < 16 * 256 * 32; e += nthr) { const int dk4 = (e & 31) * 4, dv = (e >> 5) & 255, bh = e >> 13;
;         f32x4 run = (f32x4){0.f, 0.f, 0.f, 0.f};
; #pragma unroll 16
;         for (int c = 0; c < NCH; ++c) { const size_t it = (size_t)bh * NCH + c; u16* sp = a.states + (it * 256 + dv) * 128 + dk4;
;             const f32x4 d = *(const f32x4*)(a.dec + it * 128 + dk4); const bf16x4 x = *(const bf16x4*)sp;
;             *(u32x2*)sp = pk4(run);
; #pragma unroll
;             for (int j = 0; j < 4; ++j) run[j] = d[j] * run[j] + bf2f((u16)x[j]); } }
	global_load_dwordx4 v[56:59], v[10:11], off nt
	global_load_dwordx2 v[134:135], v[24:25], off nt
	v_lshl_add_u64 v[24:25], v[24:25], 0, s[0:1]
	global_load_dwordx4 v[60:63], v[10:11], off offset:512 nt
	global_load_dwordx2 v[136:137], v[24:25], off nt
	v_lshl_add_u64 v[24:25], v[24:25], 0, s[0:1]
	global_load_dwordx4 v[64:67], v[10:11], off offset:1024 nt
	global_load_dwordx2 v[138:139], v[24:25], off nt
	v_lshl_add_u64 v[24:25], v[24:25], 0, s[0:1]
	global_load_dwordx4 v[68:71], v[10:11], off offset:1536 nt
	global_load_dwordx2 v[140:141], v[24:25], off nt
	v_lshl_add_u64 v[24:25], v[24:25], 0, s[0:1]
	global_load_dwordx4 v[72:75], v[10:11], off offset:2048 nt
	global_load_dwordx2 v[142:143], v[24:25], off nt
	v_lshl_add_u64 v[24:25], v[24:25], 0, s[0:1]
	global_load_dwordx4 v[76:79], v[10:11], off offset:2560 nt
	global_load_dwordx2 v[144:145], v[24:25], off nt
	v_lshl_add_u64 v[24:25], v[24:25], 0, s[0:1]
	global_load_dwordx4 v[80:83], v[10:11], off offset:3072 nt
	global_load_dwordx2 v[148:149], v[24:25], off nt
	v_lshl_add_u64 v[24:25], v[24:25], 0, s[0:1]
	global_load_dwordx4 v[88:91], v[10:11], off offset:3584 nt
	global_load_dwordx2 v[150:151], v[24:25], off nt
	v_lshl_add_u64 v[24:25], v[24:25], 0, s[0:1]
	v_add_co_u32_e32 v10, vcc, 0x1000, v10
	s_nop 1
	v_addc_co_u32_e32 v11, vcc, 0, v11, vcc
	v_cvt_pk_bf16_f32 v28, v12, v13
	v_cvt_pk_bf16_f32 v29, v14, v15
	global_store_dwordx2 v[26:27], v[28:29], off
	v_lshl_add_u64 v[26:27], v[26:27], 0, s[0:1]
	s_waitcnt vmcnt(39)
	v_and_b32_e32 v21, 0xffff0000, v152
	v_lshlrev_b32_e32 v20, 16, v152
	v_and_b32_e32 v23, 0xffff0000, v153
	v_lshlrev_b32_e32 v22, 16, v153
	v_pk_fma_f32 v[12:13], v[12:13], v[92:93], v[20:21]
	v_pk_fma_f32 v[14:15], v[14:15], v[94:95], v[22:23]
	v_cvt_pk_bf16_f32 v28, v12, v13
	v_cvt_pk_bf16_f32 v29, v14, v15
	global_store_dwordx2 v[26:27], v[28:29], off
	v_lshl_add_u64 v[26:27], v[26:27], 0, s[0:1]
	s_waitcnt vmcnt(38)
	v_and_b32_e32 v21, 0xffff0000, v162
	v_lshlrev_b32_e32 v20, 16, v162
	v_and_b32_e32 v23, 0xffff0000, v163
	v_lshlrev_b32_e32 v22, 16, v163
	v_pk_fma_f32 v[12:13], v[12:13], v[100:101], v[20:21]
	v_pk_fma_f32 v[14:15], v[14:15], v[102:103], v[22:23]
	v_cvt_pk_bf16_f32 v28, v12, v13
	v_cvt_pk_bf16_f32 v29, v14, v15
	global_store_dwordx2 v[26:27], v[28:29], off
	v_lshl_add_u64 v[26:27], v[26:27], 0, s[0:1]
	s_waitcnt vmcnt(37)
	v_and_b32_e32 v21, 0xffff0000, v164
	v_lshlrev_b32_e32 v20, 16, v164
	v_and_b32_e32 v23, 0xffff0000, v165
	v_lshlrev_b32_e32 v22, 16, v165
	v_pk_fma_f32 v[12:13], v[12:13], v[104:105], v[20:21]
	v_pk_fma_f32 v[14:15], v[14:15], v[106:107], v[22:23]
	v_cvt_pk_bf16_f32 v28, v12, v13
	v_cvt_pk_bf16_f32 v29, v14, v15
	global_store_dwordx2 v[26:27], v[28:29], off
	v_lshl_add_u64 v[26:27], v[26:27], 0, s[0:1]
	s_waitcnt vmcnt(36)
	v_and_b32_e32 v21, 0xffff0000, v176
	v_lshlrev_b32_e32 v20, 16, v176
	v_and_b32_e32 v23, 0xffff0000, v177
	v_lshlrev_b32_e32 v22, 16, v177
	v_pk_fma_f32 v[12:13], v[12:13], v[108:109], v[20:21]
	v_pk_fma_f32 v[14:15], v[14:15], v[110:111], v[22:23]
	v_cvt_pk_bf16_f32 v28, v12, v13
	v_cvt_pk_bf16_f32 v29, v14, v15
	global_store_dwordx2 v[26:27], v[28:29], off
	v_lshl_add_u64 v[26:27], v[26:27], 0, s[0:1]
	s_waitcnt vmcnt(35)
	v_and_b32_e32 v21, 0xffff0000, v178
	v_lshlrev_b32_e32 v20, 16, v178
	v_and_b32_e32 v23, 0xffff0000, v179
	v_lshlrev_b32_e32 v22, 16, v179
	v_pk_fma_f32 v[12:13], v[12:13], v[112:113], v[20:21]
	v_pk_fma_f32 v[14:15], v[14:15], v[114:115], v[22:23]
	v_cvt_pk_bf16_f32 v28, v12, v13
	v_cvt_pk_bf16_f32 v29, v14, v15
	global_store_dwordx2 v[26:27], v[28:29], off
	v_lshl_add_u64 v[26:27], v[26:27], 0, s[0:1]
	s_waitcnt vmcnt(34)
	v_and_b32_e32 v21, 0xffff0000, v180
	v_lshlrev_b32_e32 v20, 16, v180
	v_and_b32_e32 v23, 0xffff0000, v181
	v_lshlrev_b32_e32 v22, 16, v181
	v_pk_fma_f32 v[12:13], v[12:13], v[116:117], v[20:21]
	v_pk_fma_f32 v[14:15], v[14:15], v[118:119], v[22:23]
	v_cvt_pk_bf16_f32 v28, v12, v13
	v_cvt_pk_bf16_f32 v29, v14, v15
	global_store_dwordx2 v[26:27], v[28:29], off
	v_lshl_add_u64 v[26:27], v[26:27], 0, s[0:1]
	s_waitcnt vmcnt(33)
	v_and_b32_e32 v21, 0xffff0000, v182
	v_lshlrev_b32_e32 v20, 16, v182
	v_and_b32_e32 v23, 0xffff0000, v183
	v_lshlrev_b32_e32 v22, 16, v183
	v_pk_fma_f32 v[12:13], v[12:13], v[126:127], v[20:21]
	v_pk_fma_f32 v[14:15], v[14:15], v[128:129], v[22:23]
	v_cvt_pk_bf16_f32 v28, v12, v13
	v_cvt_pk_bf16_f32 v29, v14, v15
	global_store_dwordx2 v[26:27], v[28:29], off
	v_lshl_add_u64 v[26:27], v[26:27], 0, s[0:1]
	s_waitcnt vmcnt(32)
	v_and_b32_e32 v21, 0xffff0000, v120
	v_lshlrev_b32_e32 v20, 16, v120
	v_and_b32_e32 v23, 0xffff0000, v121
	v_lshlrev_b32_e32 v22, 16, v121
	v_pk_fma_f32 v[12:13], v[12:13], v[130:131], v[20:21]
	v_pk_fma_f32 v[14:15], v[14:15], v[132:133], v[22:23]
	s_branch .Lms_loop
